# attention A: validity masks computed arithmetically in the chunk loop instead of 64 spilled lane masks
# speedup vs baseline: 1.0055x; 1.0019x over previous
; #define LAS __attribute__((address_space(3)))
; __device__ __forceinline__ f32x4 mfma16(const bf16x8 a, const bf16x8 b, const f32x4 c) { return __builtin_amdgcn_mfma_f32_16x16x32_bf16(a, b, c, 0, 0, 0); }
; __device__ __forceinline__ void attn_a_unit(LAS unsigned char* lds, bf16_t* QKV, float* LSE, int unit) {
;     ...
;         f32x4 s[8];
; #pragma unroll
;         for (int kb = 0; kb < 8; ++kb) { f32x4 a = (f32x4){0.f, 0.f, 0.f, 0.f};
; #pragma unroll
;             for (int ds = 0; ds < 4; ++ds) { const bf16x8 kf = *(const LAS bf16x8*)(Ks + (kb * 16 + fr) * KS_PITCH + ds * 32 + fq * 8); a = mfma16(kf, qf[ds], a); }
;             s[kb] = a; }
;         const float tb = -sd2 * (float)(dq + (c == 1 ? 0 : 128));
;         float mc = -1e30f;
; #pragma unroll
;         for (int kb = 0; kb < 8; ++kb)
; #pragma unroll
;             for (int j = 0; j < 4; ++j) { const int C = kb * 16 + j;
;                 const bool valid = (c == 1) ? (C <= dq) : (C >= dq);
;                 float v = __builtin_fmaf(s[kb][j], ATT_SCALE * LOG2E, tb); v = __builtin_fmaf(sd2, (float)C, v);
;                 v = valid ? v : -1e30f; s[kb][j] = v; mc = fmaxf(mc, v); }
.LBB0_202:
	s_cmp_eq_u32 s33, 1
	v_add_u32_e32 v165, 0xd800, v115
	v_add_u32_e32 v166, 0xe800, v114
	v_add_u32_e32 v167, 0xf800, v115
	s_cselect_b32 s77, 0, 0x80
	ds_read_b128 v[116:119], v113
	ds_read_b128 v[120:123], v113 offset:64
	s_waitcnt lgkmcnt(1)
	v_mfma_f32_16x16x32_bf16 v[116:119], v[116:119], v[0:3], 0
	ds_read_b128 v[124:127], v113 offset:128
	s_waitcnt lgkmcnt(1)
	v_mfma_f32_16x16x32_bf16 v[116:119], v[120:123], v[4:7], v[116:119]
	ds_read_b128 v[120:123], v113 offset:192
	v_add_u32_e32 v129, s77, v105
	s_add_i32 s33, s33, -1
	s_waitcnt lgkmcnt(1)
	v_mfma_f32_16x16x32_bf16 v[124:127], v[124:127], v[8:11], v[116:119]
	s_nop 2
	v_cvt_f32_i32_e32 v116, v129
	s_waitcnt lgkmcnt(0)
	v_mfma_f32_16x16x32_bf16 v[118:121], v[120:123], v[12:15], v[124:127]
	v_add_u32_e32 v117, s77, v105
	v_cmp_gt_u32_e32 vcc, 0x81, v117
	v_mul_f32_e64 v116, -v104, v116
	ds_read_b128 v[128:131], v113 offset:4352
	ds_read_b128 v[132:135], v113 offset:4416
	s_nop 2
	v_fmamk_f32 v118, v118, 0x3e0293ee, v116
	v_fmac_f32_e32 v118, 0, v104
	v_cndmask_b32_e32 v125, v237, v118, vcc
	s_waitcnt lgkmcnt(1)
	v_mfma_f32_16x16x32_bf16 v[136:139], v[128:131], v[0:3], 0
	s_waitcnt lgkmcnt(0)
	v_mfma_f32_16x16x32_bf16 v[132:135], v[132:135], v[4:7], v[136:139]
	s_nop 2
	ds_read_b128 v[136:139], v113 offset:4480
	ds_read_b128 v[140:143], v113 offset:4544
	s_sub_i32 s75, s77, 1
	v_add_u32_e32 v117, s75, v105
	v_cmp_gt_u32_e32 vcc, 0x81, v117
	v_fmamk_f32 v118, v119, 0x3e0293ee, v116
	v_add_f32_e32 v118, v104, v118
	s_waitcnt lgkmcnt(1)
	v_mfma_f32_16x16x32_bf16 v[132:135], v[136:139], v[8:11], v[132:135]
	v_cndmask_b32_e32 v127, v237, v118, vcc
	s_sub_i32 s75, s77, 2
	v_add_u32_e32 v117, s75, v105
	v_cmp_gt_u32_e32 vcc, 0x81, v117
	v_fmamk_f32 v118, v120, 0x3e0293ee, v116
	v_fmac_f32_e32 v118, 2.0, v104
	v_cndmask_b32_e32 v130, v237, v118, vcc
	s_sub_i32 s75, s77, 3
	v_add_u32_e32 v117, s75, v105
	v_cmp_gt_u32_e32 vcc, 0x81, v117
	v_fmamk_f32 v118, v121, 0x3e0293ee, v116
	v_fmac_f32_e32 v118, 0x40400000, v104
	v_cndmask_b32_e32 v131, v237, v118, vcc
	s_waitcnt lgkmcnt(0)
	v_mfma_f32_16x16x32_bf16 v[118:121], v[140:143], v[12:15], v[132:135]
	s_nop 2
	ds_read_b128 v[132:135], v113 offset:8704
	ds_read_b128 v[136:139], v113 offset:8768
	s_sub_i32 s75, s77, 16
	v_add_u32_e32 v117, s75, v105
	v_cmp_gt_u32_e32 vcc, 0x81, v117
	v_fmamk_f32 v118, v118, 0x3e0293ee, v116
	v_fmac_f32_e32 v118, 0x41800000, v104
	s_waitcnt lgkmcnt(1)
	v_mfma_f32_16x16x32_bf16 v[132:135], v[132:135], v[0:3], 0
	v_cndmask_b32_e32 v148, v237, v118, vcc
	s_waitcnt lgkmcnt(0)
	v_mfma_f32_16x16x32_bf16 v[132:135], v[136:139], v[4:7], v[132:135]
	ds_read_b128 v[136:139], v113 offset:8832
	ds_read_b128 v[140:143], v113 offset:8896
	s_waitcnt lgkmcnt(1)
	v_mfma_f32_16x16x32_bf16 v[132:135], v[136:139], v[8:11], v[132:135]
	s_sub_i32 s75, s77, 17
	v_add_u32_e32 v117, s75, v105
	v_cmp_gt_u32_e32 vcc, 0x81, v117
	v_fmamk_f32 v118, v119, 0x3e0293ee, v116
	v_fmac_f32_e32 v118, 0x41880000, v104
	v_cndmask_b32_e32 v149, v237, v118, vcc
	s_sub_i32 s75, s77, 18
	v_add_u32_e32 v117, s75, v105
	v_cmp_gt_u32_e32 vcc, 0x81, v117
	v_fmamk_f32 v118, v120, 0x3e0293ee, v116
	v_fmac_f32_e32 v118, 0x41900000, v104
	v_cndmask_b32_e32 v150, v237, v118, vcc
	s_sub_i32 s75, s77, 19
	v_add_u32_e32 v117, s75, v105
	v_cmp_gt_u32_e32 vcc, 0x81, v117
	v_fmamk_f32 v118, v121, 0x3e0293ee, v116
	v_fmac_f32_e32 v118, 0x41980000, v104
	v_cndmask_b32_e32 v151, v237, v118, vcc
	s_waitcnt lgkmcnt(0)
	v_mfma_f32_16x16x32_bf16 v[118:121], v[140:143], v[12:15], v[132:135]
	s_nop 2
	ds_read_b128 v[132:135], v113 offset:13056
	ds_read_b128 v[136:139], v113 offset:13120
	s_sub_i32 s75, s77, 32
	v_add_u32_e32 v117, s75, v105
	v_cmp_gt_u32_e32 vcc, 0x81, v117
	v_fmamk_f32 v118, v118, 0x3e0293ee, v116
	v_fmac_f32_e32 v118, 0x42000000, v104
	s_waitcnt lgkmcnt(1)
	v_mfma_f32_16x16x32_bf16 v[132:135], v[132:135], v[0:3], 0
	v_cndmask_b32_e32 v152, v237, v118, vcc
	s_waitcnt lgkmcnt(0)
	v_mfma_f32_16x16x32_bf16 v[132:135], v[136:139], v[4:7], v[132:135]
	s_sub_i32 s75, s77, 33
	v_add_u32_e32 v117, s75, v105
	v_cmp_gt_u32_e32 vcc, 0x81, v117
	v_fmamk_f32 v118, v119, 0x3e0293ee, v116
	v_fmac_f32_e32 v118, 0x42040000, v104
	ds_read_b128 v[136:139], v113 offset:13184
	ds_read_b128 v[140:143], v113 offset:13248
	v_cndmask_b32_e32 v153, v237, v118, vcc
	s_sub_i32 s75, s77, 34
	v_add_u32_e32 v117, s75, v105
	v_cmp_gt_u32_e32 vcc, 0x81, v117
	v_fmamk_f32 v118, v120, 0x3e0293ee, v116
	v_fmac_f32_e32 v118, 0x42080000, v104
	s_waitcnt lgkmcnt(1)
	v_mfma_f32_16x16x32_bf16 v[132:135], v[136:139], v[8:11], v[132:135]
	v_cndmask_b32_e32 v154, v237, v118, vcc
	s_sub_i32 s75, s77, 35
	v_add_u32_e32 v117, s75, v105
	v_cmp_gt_u32_e32 vcc, 0x81, v117
	v_fmamk_f32 v118, v121, 0x3e0293ee, v116
	v_fmac_f32_e32 v118, 0x420c0000, v104
	v_cndmask_b32_e32 v155, v237, v118, vcc
	s_waitcnt lgkmcnt(0)
	v_mfma_f32_16x16x32_bf16 v[118:121], v[140:143], v[12:15], v[132:135]
	s_nop 2
	ds_read_b128 v[132:135], v113 offset:17408
	ds_read_b128 v[136:139], v113 offset:17472
	s_sub_i32 s75, s77, 48
	v_add_u32_e32 v117, s75, v105
	v_cmp_gt_u32_e32 vcc, 0x81, v117
	v_fmamk_f32 v118, v118, 0x3e0293ee, v116
	v_fmac_f32_e32 v118, 0x42400000, v104
	v_cndmask_b32_e32 v156, v237, v118, vcc
	s_waitcnt lgkmcnt(1)
	v_mfma_f32_16x16x32_bf16 v[132:135], v[132:135], v[0:3], 0
	s_sub_i32 s75, s77, 49
	v_add_u32_e32 v117, s75, v105
	v_cmp_gt_u32_e32 vcc, 0x81, v117
	v_fmamk_f32 v118, v119, 0x3e0293ee, v116
	v_fmac_f32_e32 v118, 0x42440000, v104
	s_waitcnt lgkmcnt(0)
; #define LAS __attribute__((address_space(3)))
; __device__ __forceinline__ f32x4 mfma16(const bf16x8 a, const bf16x8 b, const f32x4 c) { return __builtin_amdgcn_mfma_f32_16x16x32_bf16(a, b, c, 0, 0, 0); }
; __device__ __forceinline__ void attn_a_unit(LAS unsigned char* lds, bf16_t* QKV, float* LSE, int unit) {
;     ...
;         f32x4 s[8];
; #pragma unroll
;         for (int kb = 0; kb < 8; ++kb) { f32x4 a = (f32x4){0.f, 0.f, 0.f, 0.f};
; #pragma unroll
;             for (int ds = 0; ds < 4; ++ds) { const bf16x8 kf = *(const LAS bf16x8*)(Ks + (kb * 16 + fr) * KS_PITCH + ds * 32 + fq * 8); a = mfma16(kf, qf[ds], a); }
;             s[kb] = a; }
;         const float tb = -sd2 * (float)(dq + (c == 1 ? 0 : 128));
;         float mc = -1e30f;
; #pragma unroll
;         for (int kb = 0; kb < 8; ++kb)
; #pragma unroll
;             for (int j = 0; j < 4; ++j) { const int C = kb * 16 + j;
;                 const bool valid = (c == 1) ? (C <= dq) : (C >= dq);
;                 float v = __builtin_fmaf(s[kb][j], ATT_SCALE * LOG2E, tb); v = __builtin_fmaf(sd2, (float)C, v);
;                 v = valid ? v : -1e30f; s[kb][j] = v; mc = fmaxf(mc, v); }
	v_mfma_f32_16x16x32_bf16 v[132:135], v[136:139], v[4:7], v[132:135]
	v_cndmask_b32_e32 v157, v237, v118, vcc
	ds_read_b128 v[136:139], v113 offset:17536
	ds_read_b128 v[140:143], v113 offset:17600
	s_sub_i32 s75, s77, 50
	v_add_u32_e32 v117, s75, v105
	v_cmp_gt_u32_e32 vcc, 0x81, v117
	v_fmamk_f32 v118, v120, 0x3e0293ee, v116
	v_fmac_f32_e32 v118, 0x42480000, v104
	s_waitcnt lgkmcnt(1)
	v_mfma_f32_16x16x32_bf16 v[132:135], v[136:139], v[8:11], v[132:135]
	v_cndmask_b32_e32 v158, v237, v118, vcc
	s_sub_i32 s75, s77, 51
	v_add_u32_e32 v117, s75, v105
	v_cmp_gt_u32_e32 vcc, 0x81, v117
	v_fmamk_f32 v118, v121, 0x3e0293ee, v116
	v_fmac_f32_e32 v118, 0x424c0000, v104
	v_cndmask_b32_e32 v159, v237, v118, vcc
	s_waitcnt lgkmcnt(0)
	v_mfma_f32_16x16x32_bf16 v[118:121], v[140:143], v[12:15], v[132:135]
	s_nop 2
	ds_read_b128 v[132:135], v113 offset:21760
	ds_read_b128 v[136:139], v113 offset:21824
	s_sub_i32 s75, s77, 64
	v_add_u32_e32 v117, s75, v105
	v_cmp_gt_u32_e32 vcc, 0x81, v117
	v_fmamk_f32 v118, v118, 0x3e0293ee, v116
	s_waitcnt lgkmcnt(1)
	v_mfma_f32_16x16x32_bf16 v[132:135], v[132:135], v[0:3], 0
	v_fmac_f32_e32 v118, 0x42800000, v104
	s_waitcnt lgkmcnt(0)
	v_mfma_f32_16x16x32_bf16 v[132:135], v[136:139], v[4:7], v[132:135]
	v_cndmask_b32_e32 v160, v237, v118, vcc
	s_sub_i32 s75, s77, 0x41
	v_add_u32_e32 v117, s75, v105
	v_cmp_gt_u32_e32 vcc, 0x81, v117
	v_fmamk_f32 v118, v119, 0x3e0293ee, v116
	ds_read_b128 v[136:139], v113 offset:21888
	ds_read_b128 v[140:143], v113 offset:21952
	v_fmac_f32_e32 v118, 0x42820000, v104
	s_waitcnt lgkmcnt(1)
	v_mfma_f32_16x16x32_bf16 v[132:135], v[136:139], v[8:11], v[132:135]
	v_cndmask_b32_e32 v161, v237, v118, vcc
	s_sub_i32 s75, s77, 0x42
	v_add_u32_e32 v117, s75, v105
	v_cmp_gt_u32_e32 vcc, 0x81, v117
	v_fmamk_f32 v118, v120, 0x3e0293ee, v116
	v_fmac_f32_e32 v118, 0x42840000, v104
	s_waitcnt lgkmcnt(0)
	v_mfma_f32_16x16x32_bf16 v[132:135], v[140:143], v[12:15], v[132:135]
	v_cndmask_b32_e32 v162, v237, v118, vcc
	s_sub_i32 s75, s77, 0x43
	v_add_u32_e32 v117, s75, v105
	v_cmp_gt_u32_e32 vcc, 0x81, v117
	v_fmamk_f32 v118, v121, 0x3e0293ee, v116
	v_fmac_f32_e32 v118, 0x42860000, v104
	v_cndmask_b32_e32 v163, v237, v118, vcc
	s_sub_i32 s75, s77, 0x50
	v_add_u32_e32 v117, s75, v105
	v_cmp_gt_u32_e32 vcc, 0x81, v117
	v_fmamk_f32 v118, v132, 0x3e0293ee, v116
	v_fmac_f32_e32 v118, 0x42a00000, v104
	v_cndmask_b32_e32 v164, v237, v118, vcc
	s_sub_i32 s75, s77, 0x51
	v_add_u32_e32 v117, s75, v105
	v_cmp_gt_u32_e32 vcc, 0x81, v117
	v_fmamk_f32 v118, v133, 0x3e0293ee, v116
	v_fmac_f32_e32 v118, 0x42a20000, v104
	v_cndmask_b32_e32 v123, v237, v118, vcc
	ds_read_b128 v[118:121], v113 offset:26112
	ds_read_b128 v[136:139], v113 offset:26176
	s_waitcnt lgkmcnt(1)
	v_mfma_f32_16x16x32_bf16 v[140:143], v[118:121], v[0:3], 0
	s_waitcnt lgkmcnt(0)
	v_mfma_f32_16x16x32_bf16 v[136:139], v[136:139], v[4:7], v[140:143]
	s_nop 2
	ds_read_b128 v[140:143], v113 offset:26240
	ds_read_b128 v[144:147], v113 offset:26304
	s_sub_i32 s75, s77, 0x52
	v_add_u32_e32 v117, s75, v105
	v_cmp_gt_u32_e32 vcc, 0x81, v117
	v_fmamk_f32 v118, v134, 0x3e0293ee, v116
	v_fmac_f32_e32 v118, 0x42a40000, v104
	s_waitcnt lgkmcnt(1)
	v_mfma_f32_16x16x32_bf16 v[136:139], v[140:143], v[8:11], v[136:139]
	v_cndmask_b32_e32 v121, v237, v118, vcc
	s_sub_i32 s75, s77, 0x53
	v_add_u32_e32 v117, s75, v105
	v_cmp_gt_u32_e32 vcc, 0x81, v117
	v_fmamk_f32 v118, v135, 0x3e0293ee, v116
	s_waitcnt lgkmcnt(0)
	v_mfma_f32_16x16x32_bf16 v[132:135], v[144:147], v[12:15], v[136:139]
	s_nop 2
	ds_read_b128 v[136:139], v113 offset:30464
	ds_read_b128 v[140:143], v113 offset:30528
	v_fmac_f32_e32 v118, 0x42a60000, v104
	s_waitcnt lgkmcnt(1)
	v_mfma_f32_16x16x32_bf16 v[136:139], v[136:139], v[0:3], 0
	v_cndmask_b32_e32 v124, v237, v118, vcc
	s_sub_i32 s75, s77, 0x60
	v_add_u32_e32 v117, s75, v105
	v_cmp_gt_u32_e32 vcc, 0x81, v117
	v_fmamk_f32 v118, v132, 0x3e0293ee, v116
	v_fmac_f32_e32 v118, 0x42c00000, v104
	s_waitcnt lgkmcnt(0)
	v_mfma_f32_16x16x32_bf16 v[136:139], v[140:143], v[4:7], v[136:139]
	v_cndmask_b32_e32 v129, v237, v118, vcc
	s_sub_i32 s75, s77, 0x61
	v_add_u32_e32 v117, s75, v105
	v_cmp_gt_u32_e32 vcc, 0x81, v117
	v_fmamk_f32 v118, v133, 0x3e0293ee, v116
	ds_read_b128 v[140:143], v113 offset:30592
	ds_read_b128 v[144:147], v113 offset:30656
	v_fmac_f32_e32 v118, 0x42c20000, v104
	s_waitcnt lgkmcnt(1)
	v_mfma_f32_16x16x32_bf16 v[136:139], v[140:143], v[8:11], v[136:139]
	v_cndmask_b32_e32 v128, v237, v118, vcc
	s_sub_i32 s75, s77, 0x62
	v_add_u32_e32 v117, s75, v105
	v_cmp_gt_u32_e32 vcc, 0x81, v117
	v_fmamk_f32 v118, v134, 0x3e0293ee, v116
	v_fmac_f32_e32 v118, 0x42c40000, v104
	v_cndmask_b32_e32 v126, v237, v118, vcc
	s_sub_i32 s75, s77, 0x63
	v_add_u32_e32 v117, s75, v105
	v_cmp_gt_u32_e32 vcc, 0x81, v117
	v_fmamk_f32 v118, v135, 0x3e0293ee, v116
	s_waitcnt lgkmcnt(0)
; #define LAS __attribute__((address_space(3)))
; __device__ __forceinline__ unsigned cvt_pk_bf16(float lo, float hi) { unsigned r; asm("v_cvt_pk_bf16_f32 %0, %1, %2" : "=v"(r) : "v"(lo), "v"(hi)); return r; }
; __device__ __forceinline__ f32x4 mfma16(const bf16x8 a, const bf16x8 b, const f32x4 c) { return __builtin_amdgcn_mfma_f32_16x16x32_bf16(a, b, c, 0, 0, 0); }
; __device__ __forceinline__ void attn_a_unit(LAS unsigned char* lds, bf16_t* QKV, float* LSE, int unit) {
;     ...
;             for (int j = 0; j < 4; ++j) { const int C = kb * 16 + j;
;                 const bool valid = (c == 1) ? (C <= dq) : (C >= dq);
;                 float v = __builtin_fmaf(s[kb][j], ATT_SCALE * LOG2E, tb); v = __builtin_fmaf(sd2, (float)C, v);
;                 v = valid ? v : -1e30f; s[kb][j] = v; mc = fmaxf(mc, v); }
;         mc = fmaxf(mc, __shfl_xor(mc, 16)); mc = fmaxf(mc, __shfl_xor(mc, 32));
;         const float m_new = fmaxf(m_run, mc);
;         const float alpha = __builtin_amdgcn_exp2f(m_run - m_new);
;         m_run = m_new;
;         float lsum = 0.f;
; #pragma unroll
;         for (int kb = 0; kb < 8; ++kb)
; #pragma unroll
;             for (int j = 0; j < 4; ++j) { const float p = __builtin_amdgcn_exp2f(s[kb][j] - m_new); s[kb][j] = p; lsum += p; }
;         l_run = l_run * alpha + lsum;
; #pragma unroll
;         for (int db = 0; db < 8; ++db) o[db] *= alpha;
; #pragma unroll
;         for (int g2 = 0; g2 < 4; ++g2) {
;             u32x4 pw; pw.x = cvt_pk_bf16(s[2 * g2][0], s[2 * g2][1]); pw.y = cvt_pk_bf16(s[2 * g2][2], s[2 * g2][3]);
;             pw.z = cvt_pk_bf16(s[2 * g2 + 1][0], s[2 * g2 + 1][1]); pw.w = cvt_pk_bf16(s[2 * g2 + 1][2], s[2 * g2 + 1][3]);
;             const bf16x8 pb = __builtin_bit_cast(bf16x8, pw);
; #pragma unroll
;             for (int db = 0; db < 8; ++db) {
;                 const LAS bf16_t* vr = vsw[db & 1] + db * 16 * VT_PITCH;
;                 const u32x2 v0 = *(const LAS u32x2*)(vr + ((2 * g2) ^ ((db >> 1) & 3)) * 16), v1 = *(const LAS u32x2*)(vr + ((2 * g2 + 1) ^ ((db >> 1) & 3)) * 16);
;                 const u32x4 vw = (u32x4){v0.x, v0.y, v1.x, v1.y};
;                 o[db] = mfma16(__builtin_bit_cast(bf16x8, vw), pb, o[db]); }
	v_mfma_f32_16x16x32_bf16 v[132:135], v[144:147], v[12:15], v[136:139]
	v_fmac_f32_e32 v118, 0x42c60000, v104
	v_cndmask_b32_e32 v122, v237, v118, vcc
	s_sub_i32 s75, s77, 0x70
	v_add_u32_e32 v117, s75, v105
	v_cmp_gt_u32_e32 vcc, 0x81, v117
	s_nop 2
	v_fmamk_f32 v118, v132, 0x3e0293ee, v116
	v_fmac_f32_e32 v118, 0x42e00000, v104
	v_cndmask_b32_e32 v120, v237, v118, vcc
	s_sub_i32 s75, s77, 0x71
	v_add_u32_e32 v117, s75, v105
	v_cmp_gt_u32_e32 vcc, 0x81, v117
	v_fmamk_f32 v118, v133, 0x3e0293ee, v116
	v_fmac_f32_e32 v118, 0x42e20000, v104
	v_cndmask_b32_e32 v118, v237, v118, vcc
	s_sub_i32 s75, s77, 0x72
	v_add_u32_e32 v117, s75, v105
	v_cmp_gt_u32_e32 vcc, 0x81, v117
	v_fmamk_f32 v119, v134, 0x3e0293ee, v116
	v_fmac_f32_e32 v119, 0x42e40000, v104
	v_fmac_f32_e32 v116, 0x3e0293ee, v135
	v_cndmask_b32_e32 v119, v237, v119, vcc
	v_fmac_f32_e32 v116, 0x42e60000, v104
	s_sub_i32 s75, s77, 0x73
	v_add_u32_e32 v117, s75, v105
	v_cmp_gt_u32_e32 vcc, 0x81, v117
	s_mov_b32 s74, 0xf149f2ca
	s_nop 0
	v_cndmask_b32_e32 v117, v237, v116, vcc
	v_max3_f32 v116, v125, s74, v127
	v_max3_f32 v116, v116, v130, v131
	v_max3_f32 v116, v116, v148, v149
	v_max3_f32 v116, v116, v150, v151
	v_max3_f32 v116, v116, v152, v153
	v_max3_f32 v116, v116, v154, v155
	v_max3_f32 v116, v116, v156, v157
	v_max3_f32 v116, v116, v158, v159
	v_max3_f32 v116, v116, v160, v161
	v_max3_f32 v116, v116, v162, v163
	v_max3_f32 v116, v116, v164, v123
	v_max3_f32 v116, v116, v121, v124
	v_max3_f32 v116, v116, v129, v128
	v_max3_f32 v116, v116, v126, v122
	v_max3_f32 v116, v116, v120, v118
	v_max3_f32 v116, v116, v119, v117
	ds_bpermute_b32 v132, v106, v116
	s_and_b64 vcc, exec, s[2:3]
	s_waitcnt lgkmcnt(0)
	v_max_f32_e32 v132, v132, v132
	v_max_f32_e32 v116, v116, v132
	ds_bpermute_b32 v132, v107, v116
	s_waitcnt lgkmcnt(0)
	v_max3_f32 v116, v100, v116, v132
	v_sub_f32_e32 v125, v125, v116
	v_exp_f32_e32 v125, v125
	v_sub_f32_e32 v127, v127, v116
	v_exp_f32_e32 v127, v127
	v_sub_f32_e32 v130, v130, v116
	v_exp_f32_e32 v139, v130
	v_sub_f32_e32 v130, v131, v116
	v_exp_f32_e32 v140, v130
	v_sub_f32_e32 v131, v148, v116
	v_add_f32_e32 v130, 0, v125
	v_exp_f32_e32 v141, v131
	v_sub_f32_e32 v131, v149, v116
	v_add_f32_e32 v130, v127, v130
	v_exp_f32_e32 v142, v131
	v_sub_f32_e32 v131, v150, v116
	v_add_f32_e32 v130, v139, v130
	v_exp_f32_e32 v143, v131
	v_sub_f32_e32 v131, v151, v116
	v_add_f32_e32 v130, v140, v130
	v_exp_f32_e32 v144, v131
	v_sub_f32_e32 v131, v152, v116
	v_add_f32_e32 v130, v141, v130
	v_exp_f32_e32 v146, v131
	v_sub_f32_e32 v131, v153, v116
	v_add_f32_e32 v130, v142, v130
	v_exp_f32_e32 v147, v131
	v_sub_f32_e32 v131, v154, v116
	v_add_f32_e32 v130, v143, v130
	v_exp_f32_e32 v148, v131
	v_sub_f32_e32 v131, v155, v116
	v_add_f32_e32 v130, v144, v130
	v_exp_f32_e32 v149, v131
	v_sub_f32_e32 v131, v156, v116
	v_add_f32_e32 v130, v146, v130
	v_exp_f32_e32 v150, v131
	v_sub_f32_e32 v131, v157, v116
	v_add_f32_e32 v130, v147, v130
	v_exp_f32_e32 v151, v131
	v_sub_f32_e32 v131, v158, v116
	v_add_f32_e32 v130, v148, v130
	v_exp_f32_e32 v152, v131
	v_sub_f32_e32 v131, v159, v116
	v_add_f32_e32 v130, v149, v130
	v_exp_f32_e32 v153, v131
	v_sub_f32_e32 v131, v160, v116
	v_add_f32_e32 v130, v150, v130
	v_exp_f32_e32 v154, v131
	v_sub_f32_e32 v131, v161, v116
	v_add_f32_e32 v130, v151, v130
	v_exp_f32_e32 v155, v131
	v_sub_f32_e32 v131, v162, v116
	v_add_f32_e32 v130, v152, v130
	v_exp_f32_e32 v156, v131
	v_sub_f32_e32 v131, v163, v116
	v_add_f32_e32 v130, v153, v130
	v_exp_f32_e32 v157, v131
	v_add_f32_e32 v130, v154, v130
	v_add_f32_e32 v130, v155, v130
	v_add_f32_e32 v130, v156, v130
	v_add_f32_e32 v158, v157, v130
	v_sub_f32_e32 v130, v164, v116
	v_add_u32_e32 v160, 0x8800, v114
	v_add_u32_e32 v161, 0x9800, v115
	v_exp_f32_e32 v159, v130
	ds_read2_b64 v[130:133], v160 offset1:4
	ds_read2_b64 v[134:137], v161 offset0:32 offset1:36
	v_sub_f32_e32 v100, v100, v116
	v_exp_f32_e32 v100, v100
	v_add_u32_e32 v162, 0xa800, v114
	v_add_u32_e32 v163, 0xb800, v115
	v_cvt_pk_bf16_f32 v138, v125, v127
	v_pk_mul_f32 v[78:79], v[78:79], v[100:101] op_sel_hi:[1,0]
	v_pk_mul_f32 v[76:77], v[76:77], v[100:101] op_sel_hi:[1,0]
	v_pk_mul_f32 v[74:75], v[74:75], v[100:101] op_sel_hi:[1,0]
	v_pk_mul_f32 v[72:73], v[72:73], v[100:101] op_sel_hi:[1,0]
	v_cvt_pk_bf16_f32 v139, v139, v140
	v_cvt_pk_bf16_f32 v140, v141, v142
	v_cvt_pk_bf16_f32 v141, v143, v144
	v_add_u32_e32 v164, 0xc800, v114
	s_waitcnt lgkmcnt(1)
	v_mfma_f32_16x16x32_bf16 v[76:79], v[130:133], v[138:141], v[76:79]
	ds_read2_b64 v[130:133], v162 offset0:64 offset1:68
	v_pk_mul_f32 v[70:71], v[70:71], v[100:101] op_sel_hi:[1,0]
	v_pk_mul_f32 v[68:69], v[68:69], v[100:101] op_sel_hi:[1,0]
	s_waitcnt lgkmcnt(1)
	v_mfma_f32_16x16x32_bf16 v[72:75], v[134:137], v[138:141], v[72:75]
	ds_read2_b64 v[134:137], v163 offset0:96 offset1:100
	s_waitcnt lgkmcnt(1)
	v_mov_b32_e32 v142, v132
	v_mov_b32_e32 v143, v133
	v_mov_b32_e32 v144, v130
	v_mov_b32_e32 v145, v131
	s_waitcnt lgkmcnt(0)
	v_mov_b32_e32 v130, v136
	v_mov_b32_e32 v131, v137
	v_mov_b32_e32 v132, v134
	v_mov_b32_e32 v133, v135
	ds_read2_b64 v[134:137], v164 offset0:136 offset1:140
	v_mfma_f32_16x16x32_bf16 v[68:71], v[142:145], v[138:141], v[68:71]
	ds_read2_b64 v[142:145], v165 offset0:168 offset1:172
	v_pk_mul_f32 v[66:67], v[66:67], v[100:101] op_sel_hi:[1,0]
	v_pk_mul_f32 v[64:65], v[64:65], v[100:101] op_sel_hi:[1,0]
	v_pk_mul_f32 v[62:63], v[62:63], v[100:101] op_sel_hi:[1,0]
	v_pk_mul_f32 v[60:61], v[60:61], v[100:101] op_sel_hi:[1,0]
	v_mfma_f32_16x16x32_bf16 v[64:67], v[130:133], v[138:141], v[64:67]
	ds_read2_b64 v[130:133], v166 offset0:200 offset1:204
	v_pk_mul_f32 v[58:59], v[58:59], v[100:101] op_sel_hi:[1,0]
	v_pk_mul_f32 v[56:57], v[56:57], v[100:101] op_sel_hi:[1,0]
	s_waitcnt lgkmcnt(2)
; #define LAS __attribute__((address_space(3)))
; __device__ __forceinline__ unsigned cvt_pk_bf16(float lo, float hi) { unsigned r; asm("v_cvt_pk_bf16_f32 %0, %1, %2" : "=v"(r) : "v"(lo), "v"(hi)); return r; }
; __device__ __forceinline__ f32x4 mfma16(const bf16x8 a, const bf16x8 b, const f32x4 c) { return __builtin_amdgcn_mfma_f32_16x16x32_bf16(a, b, c, 0, 0, 0); }
; __device__ __forceinline__ void attn_a_unit(LAS unsigned char* lds, bf16_t* QKV, float* LSE, int unit) {
;     ...
;         l_run = l_run * alpha + lsum;
; #pragma unroll
;         for (int db = 0; db < 8; ++db) o[db] *= alpha;
; #pragma unroll
;         for (int g2 = 0; g2 < 4; ++g2) {
;             u32x4 pw; pw.x = cvt_pk_bf16(s[2 * g2][0], s[2 * g2][1]); pw.y = cvt_pk_bf16(s[2 * g2][2], s[2 * g2][3]);
;             pw.z = cvt_pk_bf16(s[2 * g2 + 1][0], s[2 * g2 + 1][1]); pw.w = cvt_pk_bf16(s[2 * g2 + 1][2], s[2 * g2 + 1][3]);
;             const bf16x8 pb = __builtin_bit_cast(bf16x8, pw);
; #pragma unroll
;             for (int db = 0; db < 8; ++db) {
;                 const LAS bf16_t* vr = vsw[db & 1] + db * 16 * VT_PITCH;
;                 const u32x2 v0 = *(const LAS u32x2*)(vr + ((2 * g2) ^ ((db >> 1) & 3)) * 16), v1 = *(const LAS u32x2*)(vr + ((2 * g2 + 1) ^ ((db >> 1) & 3)) * 16);
;                 const u32x4 vw = (u32x4){v0.x, v0.y, v1.x, v1.y};
;                 o[db] = mfma16(__builtin_bit_cast(bf16x8, vw), pb, o[db]); }
;         }
;         __syncthreads();
	v_mfma_f32_16x16x32_bf16 v[60:63], v[134:137], v[138:141], v[60:63]
	ds_read2_b64 v[134:137], v167 offset0:232 offset1:236
	v_pk_mul_f32 v[50:51], v[50:51], v[100:101] op_sel_hi:[1,0]
	v_pk_mul_f32 v[48:49], v[48:49], v[100:101] op_sel_hi:[1,0]
	s_waitcnt lgkmcnt(2)
	v_mfma_f32_16x16x32_bf16 v[56:59], v[142:145], v[138:141], v[56:59]
	s_waitcnt lgkmcnt(1)
	v_mov_b32_e32 v142, v132
	v_mov_b32_e32 v143, v133
	v_mov_b32_e32 v144, v130
	v_mov_b32_e32 v145, v131
	s_waitcnt lgkmcnt(0)
	v_mov_b32_e32 v130, v136
	v_mov_b32_e32 v131, v137
	v_mov_b32_e32 v132, v134
	v_mov_b32_e32 v133, v135
	ds_read2_b64 v[134:137], v160 offset0:8 offset1:12
	v_pk_mul_f32 v[54:55], v[54:55], v[100:101] op_sel_hi:[1,0]
	v_mfma_f32_16x16x32_bf16 v[48:51], v[130:133], v[138:141], v[48:51]
	ds_read2_b64 v[130:133], v161 offset0:40 offset1:44
	v_pk_mul_f32 v[52:53], v[52:53], v[100:101] op_sel_hi:[1,0]
	v_sub_f32_e32 v121, v121, v116
	v_sub_f32_e32 v123, v123, v116
	v_mfma_f32_16x16x32_bf16 v[52:55], v[142:145], v[138:141], v[52:55]
	v_cvt_pk_bf16_f32 v138, v146, v147
	v_cvt_pk_bf16_f32 v139, v148, v149
	v_cvt_pk_bf16_f32 v140, v150, v151
	v_cvt_pk_bf16_f32 v141, v152, v153
	ds_read2_b64 v[146:149], v164 offset0:128 offset1:132
	s_waitcnt lgkmcnt(2)
	v_mfma_f32_16x16x32_bf16 v[76:79], v[134:137], v[138:141], v[76:79]
	ds_read2_b64 v[134:137], v162 offset0:72 offset1:76
	v_exp_f32_e32 v151, v121
	v_sub_f32_e32 v121, v124, v116
	s_waitcnt lgkmcnt(2)
	v_mfma_f32_16x16x32_bf16 v[72:75], v[130:133], v[138:141], v[72:75]
	ds_read2_b64 v[130:133], v163 offset0:104 offset1:108
	s_waitcnt lgkmcnt(1)
	v_mov_b32_e32 v144, v134
	v_mov_b32_e32 v145, v135
	v_mov_b32_e32 v142, v136
	v_mov_b32_e32 v143, v137
	s_waitcnt lgkmcnt(0)
	v_mov_b32_e32 v134, v130
	v_mov_b32_e32 v135, v131
	v_exp_f32_e32 v152, v121
	v_sub_f32_e32 v121, v129, v116
	v_mfma_f32_16x16x32_bf16 v[64:67], v[132:135], v[138:141], v[64:67]
	ds_read2_b64 v[130:133], v166 offset0:192 offset1:196
	ds_read2_b64 v[134:137], v167 offset0:224 offset1:228
	v_exp_f32_e32 v150, v123
	v_mfma_f32_16x16x32_bf16 v[68:71], v[142:145], v[138:141], v[68:71]
	ds_read2_b64 v[142:145], v165 offset0:160 offset1:164
	s_waitcnt lgkmcnt(2)
	v_mov_b32_e32 v129, v133
	s_waitcnt lgkmcnt(1)
	v_mov_b32_e32 v133, v137
	v_mfma_f32_16x16x32_bf16 v[60:63], v[146:149], v[138:141], v[60:63]
	v_exp_f32_e32 v146, v121
	v_sub_f32_e32 v121, v128, v116
	v_mov_b32_e32 v128, v132
	s_waitcnt lgkmcnt(0)
	v_mfma_f32_16x16x32_bf16 v[56:59], v[142:145], v[138:141], v[56:59]
	v_mov_b32_e32 v132, v136
	v_exp_f32_e32 v142, v121
	v_sub_f32_e32 v121, v126, v116
	v_mfma_f32_16x16x32_bf16 v[52:55], v[128:131], v[138:141], v[52:55]
	ds_read2_b64 v[128:131], v160 offset0:16 offset1:20
	ds_read2_b64 v[124:127], v161 offset0:48 offset1:52
	v_sub_f32_e32 v120, v120, v116
	v_mfma_f32_16x16x32_bf16 v[48:51], v[132:135], v[138:141], v[48:51]
	v_cvt_pk_bf16_f32 v132, v154, v155
	v_cvt_pk_bf16_f32 v133, v156, v157
	v_cvt_pk_bf16_f32 v134, v159, v150
	v_cvt_pk_bf16_f32 v135, v151, v152
	v_exp_f32_e32 v140, v121
	s_waitcnt lgkmcnt(1)
	v_mfma_f32_16x16x32_bf16 v[76:79], v[128:131], v[132:135], v[76:79]
	ds_read2_b64 v[128:131], v162 offset0:80 offset1:84
	v_sub_f32_e32 v121, v122, v116
	v_exp_f32_e32 v141, v121
	s_waitcnt lgkmcnt(1)
	v_mfma_f32_16x16x32_bf16 v[72:75], v[124:127], v[132:135], v[72:75]
	ds_read2_b64 v[122:125], v163 offset0:112 offset1:116
	s_waitcnt lgkmcnt(1)
	v_mov_b32_e32 v126, v130
	v_mov_b32_e32 v127, v131
	v_sub_f32_e32 v118, v118, v116
	v_sub_f32_e32 v117, v117, v116
	s_waitcnt lgkmcnt(0)
	v_mov_b32_e32 v136, v124
	v_mov_b32_e32 v137, v125
	v_mov_b32_e32 v138, v122
	v_mov_b32_e32 v139, v123
	ds_read2_b64 v[122:125], v164 offset0:152 offset1:156
	v_mfma_f32_16x16x32_bf16 v[68:71], v[126:129], v[132:135], v[68:71]
	ds_read2_b64 v[126:129], v165 offset0:184 offset1:188
	v_exp_f32_e32 v117, v117
	v_add_f32_e32 v130, v159, v158
	v_mfma_f32_16x16x32_bf16 v[64:67], v[136:139], v[132:135], v[64:67]
	v_exp_f32_e32 v136, v120
	v_exp_f32_e32 v137, v118
	v_sub_f32_e32 v118, v119, v116
	s_waitcnt lgkmcnt(1)
	v_mfma_f32_16x16x32_bf16 v[60:63], v[122:125], v[132:135], v[60:63]
	ds_read2_b64 v[120:123], v166 offset0:216 offset1:220
	v_exp_f32_e32 v138, v118
	s_waitcnt lgkmcnt(0)
	v_mov_b32_e32 v118, v122
	v_mfma_f32_16x16x32_bf16 v[56:59], v[126:129], v[132:135], v[56:59]
	ds_read2_b64 v[124:127], v167 offset0:248 offset1:252
	v_mov_b32_e32 v119, v123
	v_cvt_pk_bf16_f32 v128, v136, v137
	v_cvt_pk_bf16_f32 v129, v138, v117
	s_waitcnt lgkmcnt(0)
	v_mov_b32_e32 v122, v126
	v_mov_b32_e32 v123, v127
	v_mfma_f32_16x16x32_bf16 v[52:55], v[118:121], v[132:135], v[52:55]
	ds_read2_b64 v[118:121], v160 offset0:24 offset1:28
	v_cvt_pk_bf16_f32 v126, v146, v142
	v_cvt_pk_bf16_f32 v127, v140, v141
	v_mfma_f32_16x16x32_bf16 v[48:51], v[122:125], v[132:135], v[48:51]
	ds_read2_b64 v[122:125], v161 offset0:56 offset1:60
	v_add_f32_e32 v134, v150, v130
	s_waitcnt lgkmcnt(1)
	v_mfma_f32_16x16x32_bf16 v[76:79], v[118:121], v[126:129], v[76:79]
	ds_read2_b64 v[118:121], v162 offset0:88 offset1:92
	s_waitcnt lgkmcnt(0)
	v_mov_b32_e32 v130, v120
	v_mfma_f32_16x16x32_bf16 v[72:75], v[122:125], v[126:129], v[72:75]
	ds_read2_b64 v[122:125], v163 offset0:120 offset1:124
	v_mov_b32_e32 v131, v121
	v_mov_b32_e32 v132, v118
	v_mov_b32_e32 v133, v119
	s_waitcnt lgkmcnt(0)
	v_mov_b32_e32 v118, v124
	v_mov_b32_e32 v119, v125
	v_mov_b32_e32 v120, v122
	v_mov_b32_e32 v121, v123
	ds_read2_b64 v[122:125], v164 offset0:144 offset1:148
	v_mfma_f32_16x16x32_bf16 v[68:71], v[130:133], v[126:129], v[68:71]
	v_add_f32_e32 v130, v151, v134
	v_add_f32_e32 v134, v152, v130
	ds_read2_b64 v[130:133], v165 offset0:176 offset1:180
	v_mfma_f32_16x16x32_bf16 v[64:67], v[118:121], v[126:129], v[64:67]
	v_add_f32_e32 v118, v146, v134
	v_add_f32_e32 v118, v142, v118
	v_add_f32_e32 v134, v140, v118
	s_waitcnt lgkmcnt(1)
	v_mfma_f32_16x16x32_bf16 v[60:63], v[122:125], v[126:129], v[60:63]
	v_add_f32_e32 v122, v141, v134
	ds_read2_b64 v[118:121], v166 offset0:208 offset1:212
	v_add_f32_e32 v134, v136, v122
	ds_read2_b64 v[122:125], v167 offset0:240 offset1:244
	s_waitcnt lgkmcnt(2)
	v_mfma_f32_16x16x32_bf16 v[56:59], v[130:133], v[126:129], v[56:59]
	s_waitcnt lgkmcnt(0)
	v_mov_b32_e32 v130, v120
	v_mov_b32_e32 v131, v121
	v_mov_b32_e32 v132, v118
	v_mov_b32_e32 v133, v119
	v_mov_b32_e32 v118, v124
	v_mov_b32_e32 v119, v125
	v_mov_b32_e32 v120, v122
	v_mov_b32_e32 v121, v123
	v_mfma_f32_16x16x32_bf16 v[52:55], v[130:133], v[126:129], v[52:55]
	v_add_f32_e32 v122, v137, v134
	v_add_f32_e32 v122, v138, v122
	v_add_f32_e32 v117, v117, v122
	v_mfma_f32_16x16x32_bf16 v[48:51], v[118:121], v[126:129], v[48:51]
	v_fmac_f32_e32 v117, v103, v100
	s_barrier
	s_cbranch_vccnz .LBB0_204
	v_mov_b32_e32 v103, v117
	v_mov_b32_e32 v100, v116
	s_branch .LBB0_200
